# v4 plus the same VALU-free LDS-DMA issue (SALU m0 from one base, saddr-form global_load_lds with 32-bit lane offsets) in gemm4 K-loop
# speedup vs baseline: 1.0055x; 1.0036x over previous
; #define WAIT_V(n) asm volatile("s_waitcnt vmcnt(" #n ")" ::: "memory")
; #define WAIT_L(n) asm volatile("s_waitcnt lgkmcnt(" #n ")" ::: "memory")
; #define BAR __builtin_amdgcn_s_barrier()
; #define SCHED __builtin_amdgcn_sched_barrier(0)
; #define STG_A(b, h, ptr) do { const char* _g = (ptr) + (h) * ahalf; LAS unsigned char* _l = lw + ((b) * 2 + (h)) * 16384; GLDS(_g + voa0, _l); GLDS(_g + voa1, _l + 8192); } while (0)
; #define STG_B(b, h, ptr) do { const char* _g = (ptr) + (h) * bhalf; LAS unsigned char* _l = lw + 65536 + ((b) * 2 + (h)) * 16384; GLDS(_g + vob0, _l); GLDS(_g + vob1, _l + 8192); } while (0)
; #define LDA(dst, b, h) _Pragma("unroll") for (int m = 0; m < 4; ++m) _Pragma("unroll") for (int k = 0; k < 2; ++k) dst[m][k] = *(const LAS bf16x8*)(la + ((b) * 2 + (h)) * 16384 + m * 2048 + k * 1024)
; #define LDB(dst, b, h) _Pragma("unroll") for (int n = 0; n < 2; ++n) _Pragma("unroll") for (int k = 0; k < 2; ++k) dst[n][k] = *(const LAS bf16x8*)(lb + ((b) * 2 + (h)) * 16384 + n * 2048 + k * 1024)
; template <int BMODE, class Epi, class TileFn>
; DEV void gemm_loop(LAS unsigned char* lds, const bf16_t* __restrict__ A, int lda, const bf16_t* __restrict__ B, int ldb, int K, const Epi& epi, int t0, int tstep, int tend, const TileFn& tf) {
;     ...
;     for (int tt = t0;; tt += tstep, par ^= 1) {
;         const bool has_next = tt + tstep < tend;
;         epi.prefetch(lds, brow, par, tid);
;         int nrow = brow, ncol = bcol;
;         if (has_next) tf(tt + tstep, nrow, ncol);
;         const char* nA = (const char*)(A + (size_t)nrow * lda);
;         const char* nB = BMODE == 0 ? (const char*)(B + (size_t)ncol * ldb) : (const char*)(B + (size_t)ncol * 8);
;         for (int t = 0; t < nt; t += 2) {
;             const bool last = (t == nt - 2);
;             const char* a1 = cA + (size_t)(t + 1) * 128;
;             const char* a2 = last ? nA : cA + (size_t)(t + 2) * 128;
;             const char* b2 = last ? nB : cB + (size_t)(t + 2) * bks;
;             const char* a3 = a2 + 128; const char* b3 = b2 + bks;
;             LDB(B0, 0, 0); LDB(B1, 0, 1); SCHED; LDA(At, 0, 0); STG_A(1, 1, a1);
;             WAIT_V(8); WAIT_L(0); BAR; MMA(0, 0, At, B0); MMA(0, 1, At, B1); BAR; SCHED;
;             LDA(At, 0, 1); STG_B(0, 0, b2); STG_B(0, 1, b2); STG_A(0, 0, a2);
;             WAIT_V(8); WAIT_L(0); BAR; MMA(1, 0, At, B0); MMA(1, 1, At, B1); BAR; SCHED;
.LBB0_1440:
	v_readfirstlane_b32 s100, v211
	s_mul_i32 s46, s7, 0x1600
	s_mul_hi_i32 s47, s7, 0x1600
	s_add_u32 s30, s70, s46
	s_addc_u32 s37, s71, s47
	s_mul_i32 s48, s28, 0x1600
	s_mul_hi_i32 s49, s28, 0x1600
	s_add_u32 s50, s42, s48
	s_addc_u32 s54, s43, s49
	s_add_u32 s55, s66, s8
	s_addc_u32 s74, s67, s9
	v_lshl_add_u64 v[120:121], v[200:201], 0, s[8:9]
	v_lshl_add_u64 v[122:123], v[202:203], 0, s[8:9]
	v_readlane_b32 s8, v250, 4
	s_add_u32 s75, s8, s0
	v_readlane_b32 s0, v250, 5
	s_addc_u32 s76, s0, s1
	s_mov_b32 s77, -2
	s_mov_b64 s[0:1], 0
	v_readfirstlane_b32 s101, v188
	s_nop 3
	s_cmp_lt_u32 s101, 0x100
	s_cbranch_scc1 .Lsp_1441
	s_setprio 1
.Lsp_1441:
	ds_read_b128 v[132:135], v225
	ds_read_b128 v[136:139], v225 offset:1024
	ds_read_b128 v[140:143], v225 offset:2048
	ds_read_b128 v[144:147], v225 offset:3072
	ds_read_b128 v[148:151], v225 offset:16384
	ds_read_b128 v[152:155], v225 offset:17408
	ds_read_b128 v[156:159], v225 offset:18432
	ds_read_b128 v[160:163], v225 offset:19456
	s_add_u32 s8, s55, s0
	s_addc_u32 s9, s74, s1
	s_add_u32 s8, s8, 0xc366100
	s_addc_u32 s9, s9, 0
	s_add_u32 s31, s75, s0
	s_addc_u32 s80, s76, s1
	s_cmpk_eq_i32 s0, 0x1500
	s_cselect_b32 s53, s37, s9
	s_cselect_b32 s52, s30, s8
	s_cselect_b32 s9, s54, s80
	s_cselect_b32 s8, s50, s31
	v_lshl_add_u64 v[204:205], v[120:121], 0, s[0:1]
	v_lshl_add_u64 v[240:241], v[122:123], 0, s[0:1]
	s_add_u32 m0, s100, 0xc000
	ds_read_b128 v[164:167], v226
	ds_read_b128 v[168:171], v226 offset:1024
	ds_read_b128 v[172:175], v226 offset:2048
	ds_read_b128 v[176:179], v226 offset:3072
	ds_read_b128 v[180:183], v226 offset:4096
	ds_read_b128 v[228:231], v226 offset:5120
	ds_read_b128 v[232:235], v226 offset:6144
	ds_read_b128 v[236:239], v226 offset:7168
	global_load_lds_dwordx4 v[204:205], off
	s_add_u32 m0, s100, 0xe000
	s_nop 0
	global_load_lds_dwordx4 v[240:241], off
	s_waitcnt vmcnt(8)
	s_waitcnt lgkmcnt(0)
	s_barrier
	s_waitcnt lgkmcnt(0)
	v_mfma_f32_16x16x32_bf16 v[128:131], v[132:135], v[164:167], 0
	v_mfma_f32_16x16x32_bf16 v[124:127], v[140:143], v[164:167], 0
	v_mfma_f32_16x16x32_bf16 v[108:111], v[132:135], v[172:175], 0
	v_mfma_f32_16x16x32_bf16 v[104:107], v[140:143], v[172:175], 0
	v_mfma_f32_16x16x32_bf16 v[92:95], v[132:135], v[180:183], 0
	v_mfma_f32_16x16x32_bf16 v[88:91], v[140:143], v[180:183], 0
	v_mfma_f32_16x16x32_bf16 v[76:79], v[132:135], v[232:235], 0
	v_mfma_f32_16x16x32_bf16 v[72:75], v[140:143], v[232:235], 0
	v_mfma_f32_16x16x32_bf16 v[128:131], v[136:139], v[168:171], v[128:131]
	v_mfma_f32_16x16x32_bf16 v[124:127], v[144:147], v[168:171], v[124:127]
	v_mfma_f32_16x16x32_bf16 v[108:111], v[136:139], v[176:179], v[108:111]
	v_mfma_f32_16x16x32_bf16 v[104:107], v[144:147], v[176:179], v[104:107]
	v_mfma_f32_16x16x32_bf16 v[92:95], v[136:139], v[228:231], v[92:95]
	v_mfma_f32_16x16x32_bf16 v[88:91], v[144:147], v[228:231], v[88:91]
	v_mfma_f32_16x16x32_bf16 v[76:79], v[136:139], v[236:239], v[76:79]
	v_mfma_f32_16x16x32_bf16 v[72:75], v[144:147], v[236:239], v[72:75]
	v_mfma_f32_16x16x32_bf16 v[116:119], v[148:151], v[164:167], 0
	v_mfma_f32_16x16x32_bf16 v[112:115], v[156:159], v[164:167], 0
	v_mfma_f32_16x16x32_bf16 v[100:103], v[148:151], v[172:175], 0
	v_mfma_f32_16x16x32_bf16 v[96:99], v[156:159], v[172:175], 0
	v_mfma_f32_16x16x32_bf16 v[84:87], v[148:151], v[180:183], 0
	v_mfma_f32_16x16x32_bf16 v[80:83], v[156:159], v[180:183], 0
	v_mfma_f32_16x16x32_bf16 v[68:71], v[148:151], v[232:235], 0
	v_mfma_f32_16x16x32_bf16 v[64:67], v[156:159], v[232:235], 0
	v_mfma_f32_16x16x32_bf16 v[116:119], v[152:155], v[168:171], v[116:119]
	v_mfma_f32_16x16x32_bf16 v[112:115], v[160:163], v[168:171], v[112:115]
	v_mfma_f32_16x16x32_bf16 v[100:103], v[152:155], v[176:179], v[100:103]
	v_mfma_f32_16x16x32_bf16 v[96:99], v[160:163], v[176:179], v[96:99]
	v_mfma_f32_16x16x32_bf16 v[84:87], v[152:155], v[228:231], v[84:87]
	v_mfma_f32_16x16x32_bf16 v[80:83], v[160:163], v[228:231], v[80:83]
	v_mfma_f32_16x16x32_bf16 v[68:71], v[152:155], v[236:239], v[68:71]
	v_mfma_f32_16x16x32_bf16 v[64:67], v[160:163], v[236:239], v[64:67]
	s_barrier
	ds_read_b128 v[164:167], v226 offset:16384
	ds_read_b128 v[168:171], v226 offset:17408
	ds_read_b128 v[172:175], v226 offset:18432
	ds_read_b128 v[176:179], v226 offset:19456
	ds_read_b128 v[180:183], v226 offset:20480
	ds_read_b128 v[228:231], v226 offset:21504
	ds_read_b128 v[232:235], v226 offset:22528
	ds_read_b128 v[236:239], v226 offset:23552
	s_add_u32 s80, s8, 0xb0000
	s_addc_u32 s81, s9, 0
	s_add_u32 m0, s100, 0x10000
	s_nop 0
	global_load_lds_dwordx4 v196, s[8:9]
	s_add_u32 m0, s100, 0x12000
	s_nop 0
	global_load_lds_dwordx4 v198, s[8:9]
	s_add_u32 m0, s100, 0x14000
	s_nop 0
	global_load_lds_dwordx4 v196, s[80:81]
	s_add_u32 m0, s100, 0x16000
	s_nop 0
	global_load_lds_dwordx4 v198, s[80:81]
	s_mov_b32 m0, s100
	s_nop 0
	global_load_lds_dwordx4 v184, s[52:53]
	s_add_u32 m0, s100, 0x2000
	s_nop 0
	global_load_lds_dwordx4 v186, s[52:53]
	s_waitcnt vmcnt(8)
	s_waitcnt lgkmcnt(0)
	s_barrier
; #define WAIT_V(n) asm volatile("s_waitcnt vmcnt(" #n ")" ::: "memory")
; #define WAIT_L(n) asm volatile("s_waitcnt lgkmcnt(" #n ")" ::: "memory")
; #define BAR __builtin_amdgcn_s_barrier()
; #define SCHED __builtin_amdgcn_sched_barrier(0)
; #define STG_A(b, h, ptr) do { const char* _g = (ptr) + (h) * ahalf; LAS unsigned char* _l = lw + ((b) * 2 + (h)) * 16384; GLDS(_g + voa0, _l); GLDS(_g + voa1, _l + 8192); } while (0)
; #define STG_B(b, h, ptr) do { const char* _g = (ptr) + (h) * bhalf; LAS unsigned char* _l = lw + 65536 + ((b) * 2 + (h)) * 16384; GLDS(_g + vob0, _l); GLDS(_g + vob1, _l + 8192); } while (0)
; #define LDA(dst, b, h) _Pragma("unroll") for (int m = 0; m < 4; ++m) _Pragma("unroll") for (int k = 0; k < 2; ++k) dst[m][k] = *(const LAS bf16x8*)(la + ((b) * 2 + (h)) * 16384 + m * 2048 + k * 1024)
; #define LDB(dst, b, h) _Pragma("unroll") for (int n = 0; n < 2; ++n) _Pragma("unroll") for (int k = 0; k < 2; ++k) dst[n][k] = *(const LAS bf16x8*)(lb + ((b) * 2 + (h)) * 16384 + n * 2048 + k * 1024)
; template <int BMODE, class Epi, class TileFn>
; DEV void gemm_loop(LAS unsigned char* lds, const bf16_t* __restrict__ A, int lda, const bf16_t* __restrict__ B, int ldb, int K, const Epi& epi, int t0, int tstep, int tend, const TileFn& tf) {
;     ...
;         for (int t = 0; t < nt; t += 2) {
;             const bool last = (t == nt - 2);
;             const char* a1 = cA + (size_t)(t + 1) * 128;
;             const char* a2 = last ? nA : cA + (size_t)(t + 2) * 128;
;             const char* b2 = last ? nB : cB + (size_t)(t + 2) * bks;
;             const char* a3 = a2 + 128; const char* b3 = b2 + bks;
;             LDB(B0, 0, 0); LDB(B1, 0, 1); SCHED; LDA(At, 0, 0); STG_A(1, 1, a1);
;             WAIT_V(8); WAIT_L(0); BAR; MMA(0, 0, At, B0); MMA(0, 1, At, B1); BAR; SCHED;
;             LDA(At, 0, 1); STG_B(0, 0, b2); STG_B(0, 1, b2); STG_A(0, 0, a2);
;             WAIT_V(8); WAIT_L(0); BAR; MMA(1, 0, At, B0); MMA(1, 1, At, B1); BAR; SCHED;
;             LDB(B0, 1, 0); LDB(B1, 1, 1); SCHED; LDA(At, 1, 0); STG_A(0, 1, a2);
;             WAIT_V(8); WAIT_L(0); BAR; MMA(0, 0, At, B0); MMA(0, 1, At, B1); BAR; SCHED;
	s_waitcnt lgkmcnt(0)
	v_mfma_f32_16x16x32_bf16 v[60:63], v[132:135], v[164:167], 0
	v_mfma_f32_16x16x32_bf16 v[56:59], v[140:143], v[164:167], 0
	v_mfma_f32_16x16x32_bf16 v[44:47], v[132:135], v[172:175], 0
	v_mfma_f32_16x16x32_bf16 v[40:43], v[140:143], v[172:175], 0
	v_mfma_f32_16x16x32_bf16 v[28:31], v[132:135], v[180:183], 0
	v_mfma_f32_16x16x32_bf16 v[24:27], v[140:143], v[180:183], 0
	v_mfma_f32_16x16x32_bf16 v[12:15], v[132:135], v[232:235], 0
	v_mfma_f32_16x16x32_bf16 v[8:11], v[140:143], v[232:235], 0
	v_mfma_f32_16x16x32_bf16 v[60:63], v[136:139], v[168:171], v[60:63]
	v_mfma_f32_16x16x32_bf16 v[56:59], v[144:147], v[168:171], v[56:59]
	v_mfma_f32_16x16x32_bf16 v[44:47], v[136:139], v[176:179], v[44:47]
	v_mfma_f32_16x16x32_bf16 v[40:43], v[144:147], v[176:179], v[40:43]
	v_mfma_f32_16x16x32_bf16 v[28:31], v[136:139], v[228:231], v[28:31]
	v_mfma_f32_16x16x32_bf16 v[24:27], v[144:147], v[228:231], v[24:27]
	v_mfma_f32_16x16x32_bf16 v[12:15], v[136:139], v[236:239], v[12:15]
	v_mfma_f32_16x16x32_bf16 v[8:11], v[144:147], v[236:239], v[8:11]
	v_mfma_f32_16x16x32_bf16 v[52:55], v[148:151], v[164:167], 0
	v_mfma_f32_16x16x32_bf16 v[48:51], v[156:159], v[164:167], 0
	v_mfma_f32_16x16x32_bf16 v[36:39], v[148:151], v[172:175], 0
	v_mfma_f32_16x16x32_bf16 v[32:35], v[156:159], v[172:175], 0
	v_mfma_f32_16x16x32_bf16 v[20:23], v[148:151], v[180:183], 0
	v_mfma_f32_16x16x32_bf16 v[16:19], v[156:159], v[180:183], 0
	v_mfma_f32_16x16x32_bf16 v[4:7], v[148:151], v[232:235], 0
	v_mfma_f32_16x16x32_bf16 v[0:3], v[156:159], v[232:235], 0
	v_mfma_f32_16x16x32_bf16 v[52:55], v[152:155], v[168:171], v[52:55]
	v_mfma_f32_16x16x32_bf16 v[48:51], v[160:163], v[168:171], v[48:51]
	v_mfma_f32_16x16x32_bf16 v[36:39], v[152:155], v[176:179], v[36:39]
	v_mfma_f32_16x16x32_bf16 v[32:35], v[160:163], v[176:179], v[32:35]
	v_mfma_f32_16x16x32_bf16 v[20:23], v[152:155], v[228:231], v[20:23]
	v_mfma_f32_16x16x32_bf16 v[16:19], v[160:163], v[228:231], v[16:19]
	v_mfma_f32_16x16x32_bf16 v[4:7], v[152:155], v[236:239], v[4:7]
	v_mfma_f32_16x16x32_bf16 v[0:3], v[160:163], v[236:239], v[0:3]
	s_barrier
	s_branch .Lkmid_1441
.LBB0_1441:
	ds_read_b128 v[132:135], v225
	ds_read_b128 v[136:139], v225 offset:1024
	ds_read_b128 v[140:143], v225 offset:2048
	ds_read_b128 v[144:147], v225 offset:3072
	ds_read_b128 v[148:151], v225 offset:16384
	ds_read_b128 v[152:155], v225 offset:17408
	ds_read_b128 v[156:159], v225 offset:18432
	ds_read_b128 v[160:163], v225 offset:19456
	s_add_u32 s8, s55, s0
	s_addc_u32 s9, s74, s1
	s_add_u32 s8, s8, 0xc366100
	s_addc_u32 s9, s9, 0
	s_add_u32 s31, s75, s0
	s_addc_u32 s80, s76, s1
	s_cmpk_eq_i32 s0, 0x1500
	s_cselect_b32 s53, s37, s9
	s_cselect_b32 s52, s30, s8
	s_cselect_b32 s9, s54, s80
	s_cselect_b32 s8, s50, s31
	v_lshl_add_u64 v[204:205], v[120:121], 0, s[0:1]
	v_lshl_add_u64 v[240:241], v[122:123], 0, s[0:1]
	s_add_u32 m0, s100, 0xc000
	ds_read_b128 v[164:167], v226
	ds_read_b128 v[168:171], v226 offset:1024
	ds_read_b128 v[172:175], v226 offset:2048
	ds_read_b128 v[176:179], v226 offset:3072
	ds_read_b128 v[180:183], v226 offset:4096
	ds_read_b128 v[228:231], v226 offset:5120
	ds_read_b128 v[232:235], v226 offset:6144
	ds_read_b128 v[236:239], v226 offset:7168
	global_load_lds_dwordx4 v[204:205], off
	s_add_u32 m0, s100, 0xe000
	s_nop 0
	global_load_lds_dwordx4 v[240:241], off
	s_waitcnt vmcnt(8)
	s_waitcnt lgkmcnt(0)
	s_barrier
	s_waitcnt lgkmcnt(0)
	v_mfma_f32_16x16x32_bf16 v[128:131], v[132:135], v[164:167], v[128:131]
	v_mfma_f32_16x16x32_bf16 v[124:127], v[140:143], v[164:167], v[124:127]
	v_mfma_f32_16x16x32_bf16 v[108:111], v[132:135], v[172:175], v[108:111]
	v_mfma_f32_16x16x32_bf16 v[104:107], v[140:143], v[172:175], v[104:107]
	v_mfma_f32_16x16x32_bf16 v[92:95], v[132:135], v[180:183], v[92:95]
	v_mfma_f32_16x16x32_bf16 v[88:91], v[140:143], v[180:183], v[88:91]
	v_mfma_f32_16x16x32_bf16 v[76:79], v[132:135], v[232:235], v[76:79]
	v_mfma_f32_16x16x32_bf16 v[72:75], v[140:143], v[232:235], v[72:75]
	v_mfma_f32_16x16x32_bf16 v[128:131], v[136:139], v[168:171], v[128:131]
	v_mfma_f32_16x16x32_bf16 v[124:127], v[144:147], v[168:171], v[124:127]
	v_mfma_f32_16x16x32_bf16 v[108:111], v[136:139], v[176:179], v[108:111]
	v_mfma_f32_16x16x32_bf16 v[104:107], v[144:147], v[176:179], v[104:107]
	v_mfma_f32_16x16x32_bf16 v[92:95], v[136:139], v[228:231], v[92:95]
	v_mfma_f32_16x16x32_bf16 v[88:91], v[144:147], v[228:231], v[88:91]
	v_mfma_f32_16x16x32_bf16 v[76:79], v[136:139], v[236:239], v[76:79]
	v_mfma_f32_16x16x32_bf16 v[72:75], v[144:147], v[236:239], v[72:75]
	v_mfma_f32_16x16x32_bf16 v[116:119], v[148:151], v[164:167], v[116:119]
	v_mfma_f32_16x16x32_bf16 v[112:115], v[156:159], v[164:167], v[112:115]
	v_mfma_f32_16x16x32_bf16 v[100:103], v[148:151], v[172:175], v[100:103]
	v_mfma_f32_16x16x32_bf16 v[96:99], v[156:159], v[172:175], v[96:99]
	v_mfma_f32_16x16x32_bf16 v[84:87], v[148:151], v[180:183], v[84:87]
	v_mfma_f32_16x16x32_bf16 v[80:83], v[156:159], v[180:183], v[80:83]
	v_mfma_f32_16x16x32_bf16 v[68:71], v[148:151], v[232:235], v[68:71]
	v_mfma_f32_16x16x32_bf16 v[64:67], v[156:159], v[232:235], v[64:67]
	v_mfma_f32_16x16x32_bf16 v[116:119], v[152:155], v[168:171], v[116:119]
	v_mfma_f32_16x16x32_bf16 v[112:115], v[160:163], v[168:171], v[112:115]
	v_mfma_f32_16x16x32_bf16 v[100:103], v[152:155], v[176:179], v[100:103]
	v_mfma_f32_16x16x32_bf16 v[96:99], v[160:163], v[176:179], v[96:99]
	v_mfma_f32_16x16x32_bf16 v[84:87], v[152:155], v[228:231], v[84:87]
	v_mfma_f32_16x16x32_bf16 v[80:83], v[160:163], v[228:231], v[80:83]
	v_mfma_f32_16x16x32_bf16 v[68:71], v[152:155], v[236:239], v[68:71]
	v_mfma_f32_16x16x32_bf16 v[64:67], v[160:163], v[236:239], v[64:67]
	s_barrier
; #define WAIT_V(n) asm volatile("s_waitcnt vmcnt(" #n ")" ::: "memory")
; #define WAIT_L(n) asm volatile("s_waitcnt lgkmcnt(" #n ")" ::: "memory")
; #define BAR __builtin_amdgcn_s_barrier()
; #define SCHED __builtin_amdgcn_sched_barrier(0)
; #define STG_A(b, h, ptr) do { const char* _g = (ptr) + (h) * ahalf; LAS unsigned char* _l = lw + ((b) * 2 + (h)) * 16384; GLDS(_g + voa0, _l); GLDS(_g + voa1, _l + 8192); } while (0)
; #define STG_B(b, h, ptr) do { const char* _g = (ptr) + (h) * bhalf; LAS unsigned char* _l = lw + 65536 + ((b) * 2 + (h)) * 16384; GLDS(_g + vob0, _l); GLDS(_g + vob1, _l + 8192); } while (0)
; #define LDA(dst, b, h) _Pragma("unroll") for (int m = 0; m < 4; ++m) _Pragma("unroll") for (int k = 0; k < 2; ++k) dst[m][k] = *(const LAS bf16x8*)(la + ((b) * 2 + (h)) * 16384 + m * 2048 + k * 1024)
; #define LDB(dst, b, h) _Pragma("unroll") for (int n = 0; n < 2; ++n) _Pragma("unroll") for (int k = 0; k < 2; ++k) dst[n][k] = *(const LAS bf16x8*)(lb + ((b) * 2 + (h)) * 16384 + n * 2048 + k * 1024)
; #define MMA(ai, bj, Af, Bf) do { __builtin_amdgcn_s_setprio(1); \
;     _Pragma("unroll") for (int m = 0; m < 4; ++m) _Pragma("unroll") for (int n = 0; n < 2; ++n) _Pragma("unroll") for (int k = 0; k < 2; ++k) \
;         acc[ai][bj][m][n] = __builtin_amdgcn_mfma_f32_16x16x32_bf16(Bf[n][k], Af[m][k], acc[ai][bj][m][n], 0, 0, 0); \
;     __builtin_amdgcn_s_setprio(0); } while (0)
; template <int BMODE, class Epi, class TileFn>
; DEV void gemm_loop(LAS unsigned char* lds, const bf16_t* __restrict__ A, int lda, const bf16_t* __restrict__ B, int ldb, int K, const Epi& epi, int t0, int tstep, int tend, const TileFn& tf) {
;     ...
;             LDA(At, 0, 1); STG_B(0, 0, b2); STG_B(0, 1, b2); STG_A(0, 0, a2);
;             WAIT_V(8); WAIT_L(0); BAR; MMA(1, 0, At, B0); MMA(1, 1, At, B1); BAR; SCHED;
;             LDB(B0, 1, 0); LDB(B1, 1, 1); SCHED; LDA(At, 1, 0); STG_A(0, 1, a2);
;             WAIT_V(8); WAIT_L(0); BAR; MMA(0, 0, At, B0); MMA(0, 1, At, B1); BAR; SCHED;
	ds_read_b128 v[164:167], v226 offset:16384
	ds_read_b128 v[168:171], v226 offset:17408
	ds_read_b128 v[172:175], v226 offset:18432
	ds_read_b128 v[176:179], v226 offset:19456
	ds_read_b128 v[180:183], v226 offset:20480
	ds_read_b128 v[228:231], v226 offset:21504
	ds_read_b128 v[232:235], v226 offset:22528
	ds_read_b128 v[236:239], v226 offset:23552
	s_add_u32 s80, s8, 0xb0000
	s_addc_u32 s81, s9, 0
	s_add_u32 m0, s100, 0x10000
	s_nop 0
	global_load_lds_dwordx4 v196, s[8:9]
	s_add_u32 m0, s100, 0x12000
	s_nop 0
	global_load_lds_dwordx4 v198, s[8:9]
	s_add_u32 m0, s100, 0x14000
	s_nop 0
	global_load_lds_dwordx4 v196, s[80:81]
	s_add_u32 m0, s100, 0x16000
	s_nop 0
	global_load_lds_dwordx4 v198, s[80:81]
	s_mov_b32 m0, s100
	s_nop 0
	global_load_lds_dwordx4 v184, s[52:53]
	s_add_u32 m0, s100, 0x2000
	s_nop 0
	global_load_lds_dwordx4 v186, s[52:53]
	s_waitcnt vmcnt(8)
	s_waitcnt lgkmcnt(0)
	s_barrier
	s_waitcnt lgkmcnt(0)
	v_mfma_f32_16x16x32_bf16 v[60:63], v[132:135], v[164:167], v[60:63]
	v_mfma_f32_16x16x32_bf16 v[56:59], v[140:143], v[164:167], v[56:59]
	v_mfma_f32_16x16x32_bf16 v[44:47], v[132:135], v[172:175], v[44:47]
	v_mfma_f32_16x16x32_bf16 v[40:43], v[140:143], v[172:175], v[40:43]
	v_mfma_f32_16x16x32_bf16 v[28:31], v[132:135], v[180:183], v[28:31]
	v_mfma_f32_16x16x32_bf16 v[24:27], v[140:143], v[180:183], v[24:27]
	v_mfma_f32_16x16x32_bf16 v[12:15], v[132:135], v[232:235], v[12:15]
	v_mfma_f32_16x16x32_bf16 v[8:11], v[140:143], v[232:235], v[8:11]
	v_mfma_f32_16x16x32_bf16 v[60:63], v[136:139], v[168:171], v[60:63]
	v_mfma_f32_16x16x32_bf16 v[56:59], v[144:147], v[168:171], v[56:59]
	v_mfma_f32_16x16x32_bf16 v[44:47], v[136:139], v[176:179], v[44:47]
	v_mfma_f32_16x16x32_bf16 v[40:43], v[144:147], v[176:179], v[40:43]
	v_mfma_f32_16x16x32_bf16 v[28:31], v[136:139], v[228:231], v[28:31]
	v_mfma_f32_16x16x32_bf16 v[24:27], v[144:147], v[228:231], v[24:27]
	v_mfma_f32_16x16x32_bf16 v[12:15], v[136:139], v[236:239], v[12:15]
	v_mfma_f32_16x16x32_bf16 v[8:11], v[144:147], v[236:239], v[8:11]
	v_mfma_f32_16x16x32_bf16 v[52:55], v[148:151], v[164:167], v[52:55]
	v_mfma_f32_16x16x32_bf16 v[48:51], v[156:159], v[164:167], v[48:51]
	v_mfma_f32_16x16x32_bf16 v[36:39], v[148:151], v[172:175], v[36:39]
	v_mfma_f32_16x16x32_bf16 v[32:35], v[156:159], v[172:175], v[32:35]
	v_mfma_f32_16x16x32_bf16 v[20:23], v[148:151], v[180:183], v[20:23]
	v_mfma_f32_16x16x32_bf16 v[16:19], v[156:159], v[180:183], v[16:19]
	v_mfma_f32_16x16x32_bf16 v[4:7], v[148:151], v[232:235], v[4:7]
	v_mfma_f32_16x16x32_bf16 v[0:3], v[156:159], v[232:235], v[0:3]
	v_mfma_f32_16x16x32_bf16 v[52:55], v[152:155], v[168:171], v[52:55]
	v_mfma_f32_16x16x32_bf16 v[48:51], v[160:163], v[168:171], v[48:51]
	v_mfma_f32_16x16x32_bf16 v[36:39], v[152:155], v[176:179], v[36:39]
	v_mfma_f32_16x16x32_bf16 v[32:35], v[160:163], v[176:179], v[32:35]
	v_mfma_f32_16x16x32_bf16 v[20:23], v[152:155], v[228:231], v[20:23]
	v_mfma_f32_16x16x32_bf16 v[16:19], v[160:163], v[228:231], v[16:19]
	v_mfma_f32_16x16x32_bf16 v[4:7], v[152:155], v[236:239], v[4:7]
	v_mfma_f32_16x16x32_bf16 v[0:3], v[160:163], v[236:239], v[0:3]
	s_barrier
; #define WAIT_V(n) asm volatile("s_waitcnt vmcnt(" #n ")" ::: "memory")
; #define WAIT_L(n) asm volatile("s_waitcnt lgkmcnt(" #n ")" ::: "memory")
; #define BAR __builtin_amdgcn_s_barrier()
; #define SCHED __builtin_amdgcn_sched_barrier(0)
; #define STG_A(b, h, ptr) do { const char* _g = (ptr) + (h) * ahalf; LAS unsigned char* _l = lw + ((b) * 2 + (h)) * 16384; GLDS(_g + voa0, _l); GLDS(_g + voa1, _l + 8192); } while (0)
; #define STG_B(b, h, ptr) do { const char* _g = (ptr) + (h) * bhalf; LAS unsigned char* _l = lw + 65536 + ((b) * 2 + (h)) * 16384; GLDS(_g + vob0, _l); GLDS(_g + vob1, _l + 8192); } while (0)
; #define LDA(dst, b, h) _Pragma("unroll") for (int m = 0; m < 4; ++m) _Pragma("unroll") for (int k = 0; k < 2; ++k) dst[m][k] = *(const LAS bf16x8*)(la + ((b) * 2 + (h)) * 16384 + m * 2048 + k * 1024)
; #define LDB(dst, b, h) _Pragma("unroll") for (int n = 0; n < 2; ++n) _Pragma("unroll") for (int k = 0; k < 2; ++k) dst[n][k] = *(const LAS bf16x8*)(lb + ((b) * 2 + (h)) * 16384 + n * 2048 + k * 1024)
; #define MMA(ai, bj, Af, Bf) do { __builtin_amdgcn_s_setprio(1); \
;     _Pragma("unroll") for (int m = 0; m < 4; ++m) _Pragma("unroll") for (int n = 0; n < 2; ++n) _Pragma("unroll") for (int k = 0; k < 2; ++k) \
;         acc[ai][bj][m][n] = __builtin_amdgcn_mfma_f32_16x16x32_bf16(Bf[n][k], Af[m][k], acc[ai][bj][m][n], 0, 0, 0); \
;     __builtin_amdgcn_s_setprio(0); } while (0)
; template <int BMODE, class Epi, class TileFn>
; DEV void gemm_loop(LAS unsigned char* lds, const bf16_t* __restrict__ A, int lda, const bf16_t* __restrict__ B, int ldb, int K, const Epi& epi, int t0, int tstep, int tend, const TileFn& tf) {
;     ...
;             LDB(B0, 1, 0); LDB(B1, 1, 1); SCHED; LDA(At, 1, 0); STG_A(0, 1, a2);
;             WAIT_V(8); WAIT_L(0); BAR; MMA(0, 0, At, B0); MMA(0, 1, At, B1); BAR; SCHED;
;             LDA(At, 1, 1); STG_B(1, 0, b3); STG_B(1, 1, b3); STG_A(1, 0, a3);
;             WAIT_V(8); WAIT_L(0); BAR; MMA(1, 0, At, B0); MMA(1, 1, At, B1); BAR; SCHED;
;         }
;         if (wr == 0) BAR;
;         epi(acc, brow, bcol, lds, par);
;         if (!has_next) break;
.Lkmid_1441:
	ds_read_b128 v[132:135], v225 offset:32768
	ds_read_b128 v[136:139], v225 offset:33792
	ds_read_b128 v[140:143], v225 offset:34816
	ds_read_b128 v[144:147], v225 offset:35840
	ds_read_b128 v[148:151], v225 offset:49152
	ds_read_b128 v[152:155], v225 offset:50176
	ds_read_b128 v[156:159], v225 offset:51200
	ds_read_b128 v[160:163], v225 offset:52224
	ds_read_b128 v[164:167], v226 offset:32768
	ds_read_b128 v[168:171], v226 offset:33792
	ds_read_b128 v[172:175], v226 offset:34816
	ds_read_b128 v[176:179], v226 offset:35840
	ds_read_b128 v[180:183], v226 offset:36864
	ds_read_b128 v[228:231], v226 offset:37888
	ds_read_b128 v[232:235], v226 offset:38912
	ds_read_b128 v[236:239], v226 offset:39936
	s_add_u32 s52, s52, 0xb0000
	s_addc_u32 s53, s53, 0
	s_add_u32 m0, s100, 0x4000
	s_nop 0
	global_load_lds_dwordx4 v184, s[52:53]
	s_add_u32 m0, s100, 0x6000
	s_nop 0
	global_load_lds_dwordx4 v186, s[52:53]
	s_waitcnt vmcnt(8)
	s_waitcnt lgkmcnt(0)
	s_barrier
	s_waitcnt lgkmcnt(0)
	v_mfma_f32_16x16x32_bf16 v[128:131], v[132:135], v[164:167], v[128:131]
	v_mfma_f32_16x16x32_bf16 v[124:127], v[140:143], v[164:167], v[124:127]
	v_mfma_f32_16x16x32_bf16 v[108:111], v[132:135], v[172:175], v[108:111]
	v_mfma_f32_16x16x32_bf16 v[104:107], v[140:143], v[172:175], v[104:107]
	v_mfma_f32_16x16x32_bf16 v[92:95], v[132:135], v[180:183], v[92:95]
	v_mfma_f32_16x16x32_bf16 v[88:91], v[140:143], v[180:183], v[88:91]
	v_mfma_f32_16x16x32_bf16 v[76:79], v[132:135], v[232:235], v[76:79]
	v_mfma_f32_16x16x32_bf16 v[72:75], v[140:143], v[232:235], v[72:75]
	v_mfma_f32_16x16x32_bf16 v[128:131], v[136:139], v[168:171], v[128:131]
	v_mfma_f32_16x16x32_bf16 v[124:127], v[144:147], v[168:171], v[124:127]
	v_mfma_f32_16x16x32_bf16 v[108:111], v[136:139], v[176:179], v[108:111]
	v_mfma_f32_16x16x32_bf16 v[104:107], v[144:147], v[176:179], v[104:107]
	v_mfma_f32_16x16x32_bf16 v[92:95], v[136:139], v[228:231], v[92:95]
	v_mfma_f32_16x16x32_bf16 v[88:91], v[144:147], v[228:231], v[88:91]
	v_mfma_f32_16x16x32_bf16 v[76:79], v[136:139], v[236:239], v[76:79]
	v_mfma_f32_16x16x32_bf16 v[72:75], v[144:147], v[236:239], v[72:75]
	v_mfma_f32_16x16x32_bf16 v[116:119], v[148:151], v[164:167], v[116:119]
	v_mfma_f32_16x16x32_bf16 v[112:115], v[156:159], v[164:167], v[112:115]
	v_mfma_f32_16x16x32_bf16 v[100:103], v[148:151], v[172:175], v[100:103]
	v_mfma_f32_16x16x32_bf16 v[96:99], v[156:159], v[172:175], v[96:99]
	v_mfma_f32_16x16x32_bf16 v[84:87], v[148:151], v[180:183], v[84:87]
	v_mfma_f32_16x16x32_bf16 v[80:83], v[156:159], v[180:183], v[80:83]
	v_mfma_f32_16x16x32_bf16 v[68:71], v[148:151], v[232:235], v[68:71]
	v_mfma_f32_16x16x32_bf16 v[64:67], v[156:159], v[232:235], v[64:67]
	v_mfma_f32_16x16x32_bf16 v[116:119], v[152:155], v[168:171], v[116:119]
	v_mfma_f32_16x16x32_bf16 v[112:115], v[160:163], v[168:171], v[112:115]
	v_mfma_f32_16x16x32_bf16 v[100:103], v[152:155], v[176:179], v[100:103]
	v_mfma_f32_16x16x32_bf16 v[96:99], v[160:163], v[176:179], v[96:99]
	v_mfma_f32_16x16x32_bf16 v[84:87], v[152:155], v[228:231], v[84:87]
	v_mfma_f32_16x16x32_bf16 v[80:83], v[160:163], v[228:231], v[80:83]
	v_mfma_f32_16x16x32_bf16 v[68:71], v[152:155], v[236:239], v[68:71]
	v_mfma_f32_16x16x32_bf16 v[64:67], v[160:163], v[236:239], v[64:67]
	s_barrier
	ds_read_b128 v[164:167], v226 offset:49152
	ds_read_b128 v[168:171], v226 offset:50176
	ds_read_b128 v[172:175], v226 offset:51200
	ds_read_b128 v[176:179], v226 offset:52224
	ds_read_b128 v[180:183], v226 offset:53248
	ds_read_b128 v[228:231], v226 offset:54272
	ds_read_b128 v[232:235], v226 offset:55296
	ds_read_b128 v[236:239], v226 offset:56320
	s_add_u32 s8, s8, s2
	s_addc_u32 s9, s9, s3
	s_add_u32 m0, s100, 0x18000
	s_nop 0
	global_load_lds_dwordx4 v196, s[8:9]
	s_add_u32 m0, s100, 0x1a000
	s_nop 0
	global_load_lds_dwordx4 v198, s[8:9]
	s_add_u32 s8, s8, 0xb0000
	s_addc_u32 s9, s9, 0
	s_add_u32 m0, s100, 0x1c000
	s_nop 0
	global_load_lds_dwordx4 v196, s[8:9]
	s_add_u32 m0, s100, 0x1e000
	s_nop 0
	global_load_lds_dwordx4 v198, s[8:9]
	s_sub_u32 s80, s52, 0xb0000
	s_subb_u32 s81, s53, 0
	s_add_u32 s80, s80, s2
	s_addc_u32 s81, s81, s3
	s_add_u32 m0, s100, 0x8000
	s_nop 0
	global_load_lds_dwordx4 v184, s[80:81]
	s_add_u32 m0, s100, 0xa000
	s_nop 0
	global_load_lds_dwordx4 v186, s[80:81]
	s_waitcnt vmcnt(8)
	s_waitcnt lgkmcnt(0)
	s_barrier
	s_waitcnt lgkmcnt(0)
	v_mfma_f32_16x16x32_bf16 v[60:63], v[132:135], v[164:167], v[60:63]
	v_mfma_f32_16x16x32_bf16 v[56:59], v[140:143], v[164:167], v[56:59]
	v_mfma_f32_16x16x32_bf16 v[44:47], v[132:135], v[172:175], v[44:47]
	v_mfma_f32_16x16x32_bf16 v[40:43], v[140:143], v[172:175], v[40:43]
	v_mfma_f32_16x16x32_bf16 v[28:31], v[132:135], v[180:183], v[28:31]
	v_mfma_f32_16x16x32_bf16 v[24:27], v[140:143], v[180:183], v[24:27]
	v_mfma_f32_16x16x32_bf16 v[12:15], v[132:135], v[232:235], v[12:15]
	v_mfma_f32_16x16x32_bf16 v[8:11], v[140:143], v[232:235], v[8:11]
	v_mfma_f32_16x16x32_bf16 v[60:63], v[136:139], v[168:171], v[60:63]
	v_mfma_f32_16x16x32_bf16 v[56:59], v[144:147], v[168:171], v[56:59]
	v_mfma_f32_16x16x32_bf16 v[44:47], v[136:139], v[176:179], v[44:47]
	v_mfma_f32_16x16x32_bf16 v[40:43], v[144:147], v[176:179], v[40:43]
	v_mfma_f32_16x16x32_bf16 v[28:31], v[136:139], v[228:231], v[28:31]
	v_mfma_f32_16x16x32_bf16 v[24:27], v[144:147], v[228:231], v[24:27]
	v_mfma_f32_16x16x32_bf16 v[12:15], v[136:139], v[236:239], v[12:15]
	v_mfma_f32_16x16x32_bf16 v[8:11], v[144:147], v[236:239], v[8:11]
	v_mfma_f32_16x16x32_bf16 v[52:55], v[148:151], v[164:167], v[52:55]
	v_mfma_f32_16x16x32_bf16 v[48:51], v[156:159], v[164:167], v[48:51]
	v_mfma_f32_16x16x32_bf16 v[36:39], v[148:151], v[172:175], v[36:39]
	v_mfma_f32_16x16x32_bf16 v[32:35], v[156:159], v[172:175], v[32:35]
	v_mfma_f32_16x16x32_bf16 v[20:23], v[148:151], v[180:183], v[20:23]
	v_mfma_f32_16x16x32_bf16 v[16:19], v[156:159], v[180:183], v[16:19]
	v_mfma_f32_16x16x32_bf16 v[4:7], v[148:151], v[232:235], v[4:7]
	v_mfma_f32_16x16x32_bf16 v[0:3], v[156:159], v[232:235], v[0:3]
	v_mfma_f32_16x16x32_bf16 v[52:55], v[152:155], v[168:171], v[52:55]
	v_mfma_f32_16x16x32_bf16 v[48:51], v[160:163], v[168:171], v[48:51]
	v_mfma_f32_16x16x32_bf16 v[36:39], v[152:155], v[176:179], v[36:39]
	v_mfma_f32_16x16x32_bf16 v[32:35], v[160:163], v[176:179], v[32:35]
	v_mfma_f32_16x16x32_bf16 v[20:23], v[152:155], v[228:231], v[20:23]
	v_mfma_f32_16x16x32_bf16 v[16:19], v[160:163], v[228:231], v[16:19]
	v_mfma_f32_16x16x32_bf16 v[4:7], v[152:155], v[236:239], v[4:7]
	v_mfma_f32_16x16x32_bf16 v[0:3], v[160:163], v[236:239], v[0:3]
	s_barrier
	s_add_i32 s77, s77, 2
	s_add_u32 s0, s0, 0x100
	s_addc_u32 s1, s1, 0
	s_cmp_gt_u32 s77, 41
	s_cbranch_scc0 .LBB0_1441
	s_setprio 0
	s_and_saveexec_b64 s[0:1], s[40:41]
	s_cbranch_execz .LBB0_1444
	s_barrier
